# w_out GEMM epilogue: all 16 residual-row loads of a tile issued up front into registers freed by the k-loop (was four serial load-add-store rounds)
# speedup vs baseline: 1.1995x; 1.0008x over previous
.Lgm_p5_loop:
	ds_read_b128 v[204:207], v132 offset:16384
	ds_read_b128 v[172:175], v133
	ds_read_b128 v[208:211], v132 offset:18432
	ds_read_b128 v[212:215], v132 offset:20480
	ds_read_b128 v[220:223], v132 offset:22528
	ds_read_b128 v[176:179], v133 offset:2048
	ds_read_b128 v[180:183], v133 offset:4096
	ds_read_b128 v[184:187], v133 offset:6144
	s_setprio 1
	s_waitcnt lgkmcnt(3)
	v_mfma_f32_16x16x32_bf16 v[92:95], v[204:207], v[172:175], v[92:95]
	ds_read_b128 v[224:227], v130 offset:16384
	v_mfma_f32_16x16x32_bf16 v[88:91], v[208:211], v[172:175], v[88:91]
	ds_read_b128 v[188:191], v131
	v_mfma_f32_16x16x32_bf16 v[84:87], v[212:215], v[172:175], v[84:87]
	ds_read_b128 v[230:233], v130 offset:18432
	v_mfma_f32_16x16x32_bf16 v[150:153], v[220:223], v[172:175], v[150:153]
	ds_read_b128 v[234:237], v130 offset:20480
	s_waitcnt lgkmcnt(4)
	v_mfma_f32_16x16x32_bf16 v[44:47], v[204:207], v[176:179], v[44:47]
	ds_read_b128 v[238:241], v130 offset:22528
	v_mfma_f32_16x16x32_bf16 v[40:43], v[208:211], v[176:179], v[40:43]
	ds_read_b128 v[192:195], v131 offset:2048
	v_mfma_f32_16x16x32_bf16 v[36:39], v[212:215], v[176:179], v[36:39]
	ds_read_b128 v[196:199], v131 offset:4096
	v_mfma_f32_16x16x32_bf16 v[32:35], v[220:223], v[176:179], v[32:35]
	ds_read_b128 v[200:203], v131 offset:6144
	v_mfma_f32_16x16x32_bf16 v[28:31], v[204:207], v[180:183], v[28:31]
	s_waitcnt vmcnt(8)
	ds_write_b128 v166, v[80:83] offset:32768
	v_mfma_f32_16x16x32_bf16 v[24:27], v[208:211], v[180:183], v[24:27]
	ds_write_b128 v166, v[138:141] offset:49152
	v_mfma_f32_16x16x32_bf16 v[20:23], v[212:215], v[180:183], v[20:23]
	ds_write_b128 v166, v[120:123] offset:36864
	v_mfma_f32_16x16x32_bf16 v[16:19], v[220:223], v[180:183], v[16:19]
	ds_write_b128 v166, v[142:145] offset:53248
	v_mfma_f32_16x16x32_bf16 v[12:15], v[204:207], v[184:187], v[12:15]
	ds_write_b128 v166, v[124:127] offset:40960
	v_mfma_f32_16x16x32_bf16 v[8:11], v[208:211], v[184:187], v[8:11]
	ds_write_b128 v166, v[146:149] offset:57344
	v_mfma_f32_16x16x32_bf16 v[4:7], v[212:215], v[184:187], v[4:7]
	ds_write_b128 v166, v[134:137] offset:45056
	v_mfma_f32_16x16x32_bf16 v[0:3], v[220:223], v[184:187], v[0:3]
	s_waitcnt lgkmcnt(8)
	ds_write_b128 v166, v[168:171] offset:61440
	v_mfma_f32_16x16x32_bf16 v[92:95], v[224:227], v[188:191], v[92:95]
	v_mfma_f32_16x16x32_bf16 v[88:91], v[230:233], v[188:191], v[88:91]
	v_mfma_f32_16x16x32_bf16 v[84:87], v[234:237], v[188:191], v[84:87]
	v_mfma_f32_16x16x32_bf16 v[150:153], v[238:241], v[188:191], v[150:153]
	s_waitcnt lgkmcnt(8)
	v_mfma_f32_16x16x32_bf16 v[44:47], v[224:227], v[192:195], v[44:47]
	s_waitcnt lgkmcnt(0)
	global_load_dwordx4 v[80:83], v116, s[100:101] offset:384
	v_mfma_f32_16x16x32_bf16 v[40:43], v[230:233], v[192:195], v[40:43]
	global_load_dwordx4 v[138:141], v118, s[98:99] offset:384
	v_mfma_f32_16x16x32_bf16 v[36:39], v[234:237], v[192:195], v[36:39]
	global_load_dwordx4 v[120:123], v117, s[100:101] offset:384
	v_mfma_f32_16x16x32_bf16 v[32:35], v[238:241], v[192:195], v[32:35]
	global_load_dwordx4 v[142:145], v119, s[98:99] offset:384
	v_mfma_f32_16x16x32_bf16 v[28:31], v[224:227], v[196:199], v[28:31]
	global_load_dwordx4 v[124:127], v97, s[100:101] offset:384
	v_mfma_f32_16x16x32_bf16 v[24:27], v[230:233], v[196:199], v[24:27]
	global_load_dwordx4 v[146:149], v103, s[98:99] offset:384
	v_mfma_f32_16x16x32_bf16 v[20:23], v[234:237], v[196:199], v[20:23]
	global_load_dwordx4 v[134:137], v101, s[100:101] offset:384
	v_mfma_f32_16x16x32_bf16 v[16:19], v[238:241], v[196:199], v[16:19]
	global_load_dwordx4 v[168:171], v105, s[98:99] offset:384
	v_mfma_f32_16x16x32_bf16 v[12:15], v[224:227], v[200:203], v[12:15]
	v_mfma_f32_16x16x32_bf16 v[8:11], v[230:233], v[200:203], v[8:11]
	v_mfma_f32_16x16x32_bf16 v[4:7], v[234:237], v[200:203], v[4:7]
	v_mfma_f32_16x16x32_bf16 v[0:3], v[238:241], v[200:203], v[0:3]
	s_setprio 0
	s_barrier
	ds_read_b128 v[204:207], v132 offset:49152
	ds_read_b128 v[172:175], v133 offset:32768
	ds_read_b128 v[208:211], v132 offset:51200
	ds_read_b128 v[212:215], v132 offset:53248
	ds_read_b128 v[220:223], v132 offset:55296
	ds_read_b128 v[176:179], v133 offset:34816
	ds_read_b128 v[180:183], v133 offset:36864
	ds_read_b128 v[184:187], v133 offset:38912
	s_setprio 1
	s_waitcnt lgkmcnt(3)
	v_mfma_f32_16x16x32_bf16 v[92:95], v[204:207], v[172:175], v[92:95]
	ds_read_b128 v[224:227], v130 offset:49152
	v_mfma_f32_16x16x32_bf16 v[88:91], v[208:211], v[172:175], v[88:91]
	ds_read_b128 v[188:191], v131 offset:32768
	v_mfma_f32_16x16x32_bf16 v[84:87], v[212:215], v[172:175], v[84:87]
	ds_read_b128 v[230:233], v130 offset:51200
	v_mfma_f32_16x16x32_bf16 v[150:153], v[220:223], v[172:175], v[150:153]
	ds_read_b128 v[234:237], v130 offset:53248
	s_waitcnt lgkmcnt(4)
	v_mfma_f32_16x16x32_bf16 v[44:47], v[204:207], v[176:179], v[44:47]
	ds_read_b128 v[238:241], v130 offset:55296
	v_mfma_f32_16x16x32_bf16 v[40:43], v[208:211], v[176:179], v[40:43]
	ds_read_b128 v[192:195], v131 offset:34816
	v_mfma_f32_16x16x32_bf16 v[36:39], v[212:215], v[176:179], v[36:39]
	ds_read_b128 v[196:199], v131 offset:36864
	v_mfma_f32_16x16x32_bf16 v[32:35], v[220:223], v[176:179], v[32:35]
	ds_read_b128 v[200:203], v131 offset:38912
	v_mfma_f32_16x16x32_bf16 v[28:31], v[204:207], v[180:183], v[28:31]
	s_waitcnt vmcnt(8)
	ds_write_b128 v166, v[48:51]
	v_mfma_f32_16x16x32_bf16 v[24:27], v[208:211], v[180:183], v[24:27]
	ds_write_b128 v166, v[64:67] offset:16384
	v_mfma_f32_16x16x32_bf16 v[20:23], v[212:215], v[180:183], v[20:23]
	ds_write_b128 v166, v[52:55] offset:4096
	v_mfma_f32_16x16x32_bf16 v[16:19], v[220:223], v[180:183], v[16:19]
	ds_write_b128 v166, v[68:71] offset:20480
	v_mfma_f32_16x16x32_bf16 v[12:15], v[204:207], v[184:187], v[12:15]
	ds_write_b128 v166, v[56:59] offset:8192
	v_mfma_f32_16x16x32_bf16 v[8:11], v[208:211], v[184:187], v[8:11]
	ds_write_b128 v166, v[72:75] offset:24576
	v_mfma_f32_16x16x32_bf16 v[4:7], v[212:215], v[184:187], v[4:7]
	ds_write_b128 v166, v[60:63] offset:12288
	v_mfma_f32_16x16x32_bf16 v[0:3], v[220:223], v[184:187], v[0:3]
	s_waitcnt lgkmcnt(8)
	ds_write_b128 v166, v[76:79] offset:28672
	v_mfma_f32_16x16x32_bf16 v[92:95], v[224:227], v[188:191], v[92:95]
	v_mfma_f32_16x16x32_bf16 v[88:91], v[230:233], v[188:191], v[88:91]
	v_mfma_f32_16x16x32_bf16 v[84:87], v[234:237], v[188:191], v[84:87]
	v_mfma_f32_16x16x32_bf16 v[150:153], v[238:241], v[188:191], v[150:153]
	s_waitcnt lgkmcnt(8)
	v_mfma_f32_16x16x32_bf16 v[44:47], v[224:227], v[192:195], v[44:47]
	s_waitcnt lgkmcnt(0)
	global_load_dwordx4 v[48:51], v116, s[100:101] offset:512
	v_mfma_f32_16x16x32_bf16 v[40:43], v[230:233], v[192:195], v[40:43]
	global_load_dwordx4 v[64:67], v118, s[98:99] offset:512
	v_mfma_f32_16x16x32_bf16 v[36:39], v[234:237], v[192:195], v[36:39]
	global_load_dwordx4 v[52:55], v117, s[100:101] offset:512
	v_mfma_f32_16x16x32_bf16 v[32:35], v[238:241], v[192:195], v[32:35]
	global_load_dwordx4 v[68:71], v119, s[98:99] offset:512
	v_mfma_f32_16x16x32_bf16 v[28:31], v[224:227], v[196:199], v[28:31]
	global_load_dwordx4 v[56:59], v97, s[100:101] offset:512
	v_mfma_f32_16x16x32_bf16 v[24:27], v[230:233], v[196:199], v[24:27]
	global_load_dwordx4 v[72:75], v103, s[98:99] offset:512
	v_mfma_f32_16x16x32_bf16 v[20:23], v[234:237], v[196:199], v[20:23]
	global_load_dwordx4 v[60:63], v101, s[100:101] offset:512
	v_mfma_f32_16x16x32_bf16 v[16:19], v[238:241], v[196:199], v[16:19]
	global_load_dwordx4 v[76:79], v105, s[98:99] offset:512
	v_mfma_f32_16x16x32_bf16 v[12:15], v[224:227], v[200:203], v[12:15]
	v_mfma_f32_16x16x32_bf16 v[8:11], v[230:233], v[200:203], v[8:11]
	v_mfma_f32_16x16x32_bf16 v[4:7], v[234:237], v[200:203], v[4:7]
	v_mfma_f32_16x16x32_bf16 v[0:3], v[238:241], v[200:203], v[0:3]
	s_setprio 0
	s_barrier
	s_add_u32 s100, s100, 0x100
	s_addc_u32 s101, s101, 0
	s_add_u32 s98, s98, 0x100
	s_addc_u32 s99, s99, 0
	s_sub_u32 s94, s94, 1
	s_cmp_lg_u32 s94, 0
	s_cbranch_scc1 .Lgm_p5_loop
	ds_read_b128 v[204:207], v132 offset:16384
	ds_read_b128 v[172:175], v133
	ds_read_b128 v[208:211], v132 offset:18432
	ds_read_b128 v[212:215], v132 offset:20480
	ds_read_b128 v[220:223], v132 offset:22528
	ds_read_b128 v[176:179], v133 offset:2048
	ds_read_b128 v[180:183], v133 offset:4096
	ds_read_b128 v[184:187], v133 offset:6144
	s_setprio 1
	s_waitcnt lgkmcnt(3)
	v_mfma_f32_16x16x32_bf16 v[92:95], v[204:207], v[172:175], v[92:95]
	ds_read_b128 v[224:227], v130 offset:16384
	v_mfma_f32_16x16x32_bf16 v[88:91], v[208:211], v[172:175], v[88:91]
	ds_read_b128 v[188:191], v131
	v_mfma_f32_16x16x32_bf16 v[84:87], v[212:215], v[172:175], v[84:87]
	ds_read_b128 v[230:233], v130 offset:18432
	v_mfma_f32_16x16x32_bf16 v[150:153], v[220:223], v[172:175], v[150:153]
	ds_read_b128 v[234:237], v130 offset:20480
	s_waitcnt lgkmcnt(4)
	v_mfma_f32_16x16x32_bf16 v[44:47], v[204:207], v[176:179], v[44:47]
	ds_read_b128 v[238:241], v130 offset:22528
	v_mfma_f32_16x16x32_bf16 v[40:43], v[208:211], v[176:179], v[40:43]
	ds_read_b128 v[192:195], v131 offset:2048
	v_mfma_f32_16x16x32_bf16 v[36:39], v[212:215], v[176:179], v[36:39]
	ds_read_b128 v[196:199], v131 offset:4096
	v_mfma_f32_16x16x32_bf16 v[32:35], v[220:223], v[176:179], v[32:35]
	ds_read_b128 v[200:203], v131 offset:6144
	v_mfma_f32_16x16x32_bf16 v[28:31], v[204:207], v[180:183], v[28:31]
	s_waitcnt vmcnt(8)
	ds_write_b128 v166, v[80:83] offset:32768
	v_mfma_f32_16x16x32_bf16 v[24:27], v[208:211], v[180:183], v[24:27]
	ds_write_b128 v166, v[138:141] offset:49152
	v_mfma_f32_16x16x32_bf16 v[20:23], v[212:215], v[180:183], v[20:23]
	ds_write_b128 v166, v[120:123] offset:36864
	v_mfma_f32_16x16x32_bf16 v[16:19], v[220:223], v[180:183], v[16:19]
	ds_write_b128 v166, v[142:145] offset:53248
	v_mfma_f32_16x16x32_bf16 v[12:15], v[204:207], v[184:187], v[12:15]
	ds_write_b128 v166, v[124:127] offset:40960
	v_mfma_f32_16x16x32_bf16 v[8:11], v[208:211], v[184:187], v[8:11]
	ds_write_b128 v166, v[146:149] offset:57344
	v_mfma_f32_16x16x32_bf16 v[4:7], v[212:215], v[184:187], v[4:7]
	ds_write_b128 v166, v[134:137] offset:45056
	v_mfma_f32_16x16x32_bf16 v[0:3], v[220:223], v[184:187], v[0:3]
	s_waitcnt lgkmcnt(8)
	ds_write_b128 v166, v[168:171] offset:61440
	v_mfma_f32_16x16x32_bf16 v[92:95], v[224:227], v[188:191], v[92:95]
	v_mfma_f32_16x16x32_bf16 v[88:91], v[230:233], v[188:191], v[88:91]
	v_mfma_f32_16x16x32_bf16 v[84:87], v[234:237], v[188:191], v[84:87]
	v_mfma_f32_16x16x32_bf16 v[150:153], v[238:241], v[188:191], v[150:153]
	s_waitcnt lgkmcnt(8)
	v_mfma_f32_16x16x32_bf16 v[44:47], v[224:227], v[192:195], v[44:47]
	s_waitcnt lgkmcnt(0)
	global_load_dwordx4 v[80:83], v116, s[100:101] offset:384
	v_mfma_f32_16x16x32_bf16 v[40:43], v[230:233], v[192:195], v[40:43]
	global_load_dwordx4 v[138:141], v118, s[98:99] offset:384
	v_mfma_f32_16x16x32_bf16 v[36:39], v[234:237], v[192:195], v[36:39]
	global_load_dwordx4 v[120:123], v117, s[100:101] offset:384
	v_mfma_f32_16x16x32_bf16 v[32:35], v[238:241], v[192:195], v[32:35]
	global_load_dwordx4 v[142:145], v119, s[98:99] offset:384
	v_mfma_f32_16x16x32_bf16 v[28:31], v[224:227], v[196:199], v[28:31]
	global_load_dwordx4 v[124:127], v97, s[100:101] offset:384
	v_mfma_f32_16x16x32_bf16 v[24:27], v[230:233], v[196:199], v[24:27]
	global_load_dwordx4 v[146:149], v103, s[98:99] offset:384
	v_mfma_f32_16x16x32_bf16 v[20:23], v[234:237], v[196:199], v[20:23]
	global_load_dwordx4 v[134:137], v101, s[100:101] offset:384
	v_mfma_f32_16x16x32_bf16 v[16:19], v[238:241], v[196:199], v[16:19]
	global_load_dwordx4 v[168:171], v105, s[98:99] offset:384
	v_mfma_f32_16x16x32_bf16 v[12:15], v[224:227], v[200:203], v[12:15]
	v_mfma_f32_16x16x32_bf16 v[8:11], v[230:233], v[200:203], v[8:11]
	v_mfma_f32_16x16x32_bf16 v[4:7], v[234:237], v[200:203], v[4:7]
	v_mfma_f32_16x16x32_bf16 v[0:3], v[238:241], v[200:203], v[0:3]
	s_setprio 0
	s_barrier
	ds_read_b128 v[204:207], v132 offset:49152
	ds_read_b128 v[172:175], v133 offset:32768
	ds_read_b128 v[208:211], v132 offset:51200
	ds_read_b128 v[212:215], v132 offset:53248
	ds_read_b128 v[220:223], v132 offset:55296
	ds_read_b128 v[176:179], v133 offset:34816
	ds_read_b128 v[180:183], v133 offset:36864
	ds_read_b128 v[184:187], v133 offset:38912
	s_setprio 1
	s_waitcnt lgkmcnt(3)
	v_mfma_f32_16x16x32_bf16 v[92:95], v[204:207], v[172:175], v[92:95]
	ds_read_b128 v[224:227], v130 offset:49152
	v_mfma_f32_16x16x32_bf16 v[88:91], v[208:211], v[172:175], v[88:91]
	ds_read_b128 v[188:191], v131 offset:32768
	v_mfma_f32_16x16x32_bf16 v[84:87], v[212:215], v[172:175], v[84:87]
	ds_read_b128 v[230:233], v130 offset:51200
	v_mfma_f32_16x16x32_bf16 v[150:153], v[220:223], v[172:175], v[150:153]
	ds_read_b128 v[234:237], v130 offset:53248
	s_waitcnt lgkmcnt(4)
	v_mfma_f32_16x16x32_bf16 v[44:47], v[204:207], v[176:179], v[44:47]
	ds_read_b128 v[238:241], v130 offset:55296
	v_mfma_f32_16x16x32_bf16 v[40:43], v[208:211], v[176:179], v[40:43]
	ds_read_b128 v[192:195], v131 offset:34816
	v_mfma_f32_16x16x32_bf16 v[36:39], v[212:215], v[176:179], v[36:39]
	ds_read_b128 v[196:199], v131 offset:36864
	v_mfma_f32_16x16x32_bf16 v[32:35], v[220:223], v[176:179], v[32:35]
	ds_read_b128 v[200:203], v131 offset:38912
	v_mfma_f32_16x16x32_bf16 v[28:31], v[204:207], v[180:183], v[28:31]
	s_waitcnt vmcnt(8)
	ds_write_b128 v166, v[48:51]
	v_mfma_f32_16x16x32_bf16 v[24:27], v[208:211], v[180:183], v[24:27]
	ds_write_b128 v166, v[64:67] offset:16384
	v_mfma_f32_16x16x32_bf16 v[20:23], v[212:215], v[180:183], v[20:23]
	ds_write_b128 v166, v[52:55] offset:4096
	v_mfma_f32_16x16x32_bf16 v[16:19], v[220:223], v[180:183], v[16:19]
	ds_write_b128 v166, v[68:71] offset:20480
	v_mfma_f32_16x16x32_bf16 v[12:15], v[204:207], v[184:187], v[12:15]
	ds_write_b128 v166, v[56:59] offset:8192
	v_mfma_f32_16x16x32_bf16 v[8:11], v[208:211], v[184:187], v[8:11]
	ds_write_b128 v166, v[72:75] offset:24576
	v_mfma_f32_16x16x32_bf16 v[4:7], v[212:215], v[184:187], v[4:7]
	ds_write_b128 v166, v[60:63] offset:12288
	v_mfma_f32_16x16x32_bf16 v[0:3], v[220:223], v[184:187], v[0:3]
	s_waitcnt lgkmcnt(8)
	ds_write_b128 v166, v[76:79] offset:28672
	v_mfma_f32_16x16x32_bf16 v[92:95], v[224:227], v[188:191], v[92:95]
	v_mfma_f32_16x16x32_bf16 v[88:91], v[230:233], v[188:191], v[88:91]
	v_mfma_f32_16x16x32_bf16 v[84:87], v[234:237], v[188:191], v[84:87]
	v_mfma_f32_16x16x32_bf16 v[150:153], v[238:241], v[188:191], v[150:153]
	s_waitcnt lgkmcnt(8)
	v_mfma_f32_16x16x32_bf16 v[44:47], v[224:227], v[192:195], v[44:47]
	v_mfma_f32_16x16x32_bf16 v[40:43], v[230:233], v[192:195], v[40:43]
	v_mfma_f32_16x16x32_bf16 v[36:39], v[234:237], v[192:195], v[36:39]
	v_mfma_f32_16x16x32_bf16 v[32:35], v[238:241], v[192:195], v[32:35]
	v_mfma_f32_16x16x32_bf16 v[28:31], v[224:227], v[196:199], v[28:31]
	v_mfma_f32_16x16x32_bf16 v[24:27], v[230:233], v[196:199], v[24:27]
	v_mfma_f32_16x16x32_bf16 v[20:23], v[234:237], v[196:199], v[20:23]
	v_mfma_f32_16x16x32_bf16 v[16:19], v[238:241], v[196:199], v[16:19]
	v_mfma_f32_16x16x32_bf16 v[12:15], v[224:227], v[200:203], v[12:15]
	v_mfma_f32_16x16x32_bf16 v[8:11], v[230:233], v[200:203], v[8:11]
	v_mfma_f32_16x16x32_bf16 v[4:7], v[234:237], v[200:203], v[4:7]
	v_mfma_f32_16x16x32_bf16 v[0:3], v[238:241], v[200:203], v[0:3]
	s_setprio 0
	s_waitcnt lgkmcnt(0)
	s_barrier
	ds_read_b128 v[204:207], v132 offset:16384
	ds_read_b128 v[172:175], v133
	ds_read_b128 v[208:211], v132 offset:18432
	ds_read_b128 v[212:215], v132 offset:20480
	ds_read_b128 v[220:223], v132 offset:22528
	ds_read_b128 v[176:179], v133 offset:2048
	ds_read_b128 v[180:183], v133 offset:4096
	ds_read_b128 v[184:187], v133 offset:6144
	s_setprio 1
	s_waitcnt lgkmcnt(3)
	v_mfma_f32_16x16x32_bf16 v[92:95], v[204:207], v[172:175], v[92:95]
	ds_read_b128 v[224:227], v130 offset:16384
	v_mfma_f32_16x16x32_bf16 v[88:91], v[208:211], v[172:175], v[88:91]
	ds_read_b128 v[188:191], v131
	v_mfma_f32_16x16x32_bf16 v[84:87], v[212:215], v[172:175], v[84:87]
	ds_read_b128 v[230:233], v130 offset:18432
	v_mfma_f32_16x16x32_bf16 v[150:153], v[220:223], v[172:175], v[150:153]
	ds_read_b128 v[234:237], v130 offset:20480
	s_waitcnt lgkmcnt(4)
	v_mfma_f32_16x16x32_bf16 v[44:47], v[204:207], v[176:179], v[44:47]
	ds_read_b128 v[238:241], v130 offset:22528
	v_mfma_f32_16x16x32_bf16 v[40:43], v[208:211], v[176:179], v[40:43]
	ds_read_b128 v[192:195], v131 offset:2048
	v_mfma_f32_16x16x32_bf16 v[36:39], v[212:215], v[176:179], v[36:39]
	ds_read_b128 v[196:199], v131 offset:4096
	v_mfma_f32_16x16x32_bf16 v[32:35], v[220:223], v[176:179], v[32:35]
	ds_read_b128 v[200:203], v131 offset:6144
	v_mfma_f32_16x16x32_bf16 v[28:31], v[204:207], v[180:183], v[28:31]
	s_waitcnt vmcnt(0)
	ds_write_b128 v166, v[80:83] offset:32768
	v_mfma_f32_16x16x32_bf16 v[24:27], v[208:211], v[180:183], v[24:27]
	ds_write_b128 v166, v[138:141] offset:49152
	v_mfma_f32_16x16x32_bf16 v[20:23], v[212:215], v[180:183], v[20:23]
	ds_write_b128 v166, v[120:123] offset:36864
	v_mfma_f32_16x16x32_bf16 v[16:19], v[220:223], v[180:183], v[16:19]
	ds_write_b128 v166, v[142:145] offset:53248
	v_mfma_f32_16x16x32_bf16 v[12:15], v[204:207], v[184:187], v[12:15]
	ds_write_b128 v166, v[124:127] offset:40960
	v_mfma_f32_16x16x32_bf16 v[8:11], v[208:211], v[184:187], v[8:11]
	ds_write_b128 v166, v[146:149] offset:57344
	v_mfma_f32_16x16x32_bf16 v[4:7], v[212:215], v[184:187], v[4:7]
	ds_write_b128 v166, v[134:137] offset:45056
	v_mfma_f32_16x16x32_bf16 v[0:3], v[220:223], v[184:187], v[0:3]
	s_waitcnt lgkmcnt(8)
	ds_write_b128 v166, v[168:171] offset:61440
	v_mfma_f32_16x16x32_bf16 v[92:95], v[224:227], v[188:191], v[92:95]
	v_mfma_f32_16x16x32_bf16 v[88:91], v[230:233], v[188:191], v[88:91]
	v_mfma_f32_16x16x32_bf16 v[84:87], v[234:237], v[188:191], v[84:87]
	v_mfma_f32_16x16x32_bf16 v[150:153], v[238:241], v[188:191], v[150:153]
	s_waitcnt lgkmcnt(8)
	v_mfma_f32_16x16x32_bf16 v[44:47], v[224:227], v[192:195], v[44:47]
	v_mfma_f32_16x16x32_bf16 v[40:43], v[230:233], v[192:195], v[40:43]
	v_mfma_f32_16x16x32_bf16 v[36:39], v[234:237], v[192:195], v[36:39]
	v_mfma_f32_16x16x32_bf16 v[32:35], v[238:241], v[192:195], v[32:35]
	v_mfma_f32_16x16x32_bf16 v[28:31], v[224:227], v[196:199], v[28:31]
	v_mfma_f32_16x16x32_bf16 v[24:27], v[230:233], v[196:199], v[24:27]
	v_mfma_f32_16x16x32_bf16 v[20:23], v[234:237], v[196:199], v[20:23]
	v_mfma_f32_16x16x32_bf16 v[16:19], v[238:241], v[196:199], v[16:19]
	v_mfma_f32_16x16x32_bf16 v[12:15], v[224:227], v[200:203], v[12:15]
	v_mfma_f32_16x16x32_bf16 v[8:11], v[230:233], v[200:203], v[8:11]
	v_mfma_f32_16x16x32_bf16 v[4:7], v[234:237], v[200:203], v[4:7]
	v_mfma_f32_16x16x32_bf16 v[0:3], v[238:241], v[200:203], v[0:3]
	s_setprio 0
	s_waitcnt lgkmcnt(0)
	s_barrier
	ds_read_b128 v[204:207], v132 offset:49152
	ds_read_b128 v[172:175], v133 offset:32768
	ds_read_b128 v[208:211], v132 offset:51200
	ds_read_b128 v[212:215], v132 offset:53248
	ds_read_b128 v[220:223], v132 offset:55296
	ds_read_b128 v[176:179], v133 offset:34816
	ds_read_b128 v[180:183], v133 offset:36864
	ds_read_b128 v[184:187], v133 offset:38912
	s_setprio 1
	s_waitcnt lgkmcnt(3)
	v_mfma_f32_16x16x32_bf16 v[92:95], v[204:207], v[172:175], v[92:95]
	ds_read_b128 v[224:227], v130 offset:49152
	v_mfma_f32_16x16x32_bf16 v[88:91], v[208:211], v[172:175], v[88:91]
	ds_read_b128 v[188:191], v131 offset:32768
	v_mfma_f32_16x16x32_bf16 v[84:87], v[212:215], v[172:175], v[84:87]
	ds_read_b128 v[230:233], v130 offset:51200
	v_mfma_f32_16x16x32_bf16 v[150:153], v[220:223], v[172:175], v[150:153]
	ds_read_b128 v[234:237], v130 offset:53248
	s_waitcnt lgkmcnt(4)
	v_mfma_f32_16x16x32_bf16 v[44:47], v[204:207], v[176:179], v[44:47]
	ds_read_b128 v[238:241], v130 offset:55296
	v_mfma_f32_16x16x32_bf16 v[40:43], v[208:211], v[176:179], v[40:43]
	ds_read_b128 v[192:195], v131 offset:34816
	v_mfma_f32_16x16x32_bf16 v[36:39], v[212:215], v[176:179], v[36:39]
	ds_read_b128 v[196:199], v131 offset:36864
	v_mfma_f32_16x16x32_bf16 v[32:35], v[220:223], v[176:179], v[32:35]
	ds_read_b128 v[200:203], v131 offset:38912
	v_mfma_f32_16x16x32_bf16 v[28:31], v[204:207], v[180:183], v[28:31]
	v_mfma_f32_16x16x32_bf16 v[24:27], v[208:211], v[180:183], v[24:27]
	v_mfma_f32_16x16x32_bf16 v[20:23], v[212:215], v[180:183], v[20:23]
	v_mfma_f32_16x16x32_bf16 v[16:19], v[220:223], v[180:183], v[16:19]
	v_mfma_f32_16x16x32_bf16 v[12:15], v[204:207], v[184:187], v[12:15]
	v_mfma_f32_16x16x32_bf16 v[8:11], v[208:211], v[184:187], v[8:11]
	v_mfma_f32_16x16x32_bf16 v[4:7], v[212:215], v[184:187], v[4:7]
	v_mfma_f32_16x16x32_bf16 v[0:3], v[220:223], v[184:187], v[0:3]
	s_waitcnt lgkmcnt(3)
	v_mfma_f32_16x16x32_bf16 v[92:95], v[224:227], v[188:191], v[92:95]
	v_mfma_f32_16x16x32_bf16 v[88:91], v[230:233], v[188:191], v[88:91]
	v_mfma_f32_16x16x32_bf16 v[84:87], v[234:237], v[188:191], v[84:87]
	v_mfma_f32_16x16x32_bf16 v[150:153], v[238:241], v[188:191], v[150:153]
	s_waitcnt lgkmcnt(0)
	v_mfma_f32_16x16x32_bf16 v[44:47], v[224:227], v[192:195], v[44:47]
	v_mfma_f32_16x16x32_bf16 v[40:43], v[230:233], v[192:195], v[40:43]
	v_mfma_f32_16x16x32_bf16 v[36:39], v[234:237], v[192:195], v[36:39]
	v_mfma_f32_16x16x32_bf16 v[32:35], v[238:241], v[192:195], v[32:35]
	v_mfma_f32_16x16x32_bf16 v[28:31], v[224:227], v[196:199], v[28:31]
	v_mfma_f32_16x16x32_bf16 v[24:27], v[230:233], v[196:199], v[24:27]
	v_mfma_f32_16x16x32_bf16 v[20:23], v[234:237], v[196:199], v[20:23]
	v_mfma_f32_16x16x32_bf16 v[16:19], v[238:241], v[196:199], v[16:19]
	v_mfma_f32_16x16x32_bf16 v[12:15], v[224:227], v[200:203], v[12:15]
	v_mfma_f32_16x16x32_bf16 v[8:11], v[230:233], v[200:203], v[8:11]
	v_mfma_f32_16x16x32_bf16 v[4:7], v[234:237], v[200:203], v[4:7]
	v_mfma_f32_16x16x32_bf16 v[0:3], v[238:241], v[200:203], v[0:3]
	s_setprio 0
	s_nop 7
	v_readlane_b32 s98, v252, 8
	v_readlane_b32 s99, v252, 9
	v_add_u32_e32 v204, s5, v167
	s_lshl_b32 s100, s4, 2
	v_lshlrev_b32_e32 v204, 12, v204
	v_lshl_add_u32 v204, v102, 2, v204
	v_lshl_add_u32 v204, v104, 2, v204
	v_add_u32_e32 v204, s100, v204
	v_add_u32_e32 v205, 0x10000, v204
	v_add_u32_e32 v206, 0x10000, v205
	v_add_u32_e32 v207, 0x10000, v206
	global_load_dwordx4 v[80:83], v204, s[98:99] offset:0
	global_load_dwordx4 v[120:123], v204, s[98:99] offset:64
	global_load_dwordx4 v[124:127], v204, s[98:99] offset:128
	global_load_dwordx4 v[134:137], v204, s[98:99] offset:192
	global_load_dwordx4 v[138:141], v205, s[98:99] offset:0
	global_load_dwordx4 v[142:145], v205, s[98:99] offset:64
	global_load_dwordx4 v[146:149], v205, s[98:99] offset:128
	global_load_dwordx4 v[168:171], v205, s[98:99] offset:192
	global_load_dwordx4 v[172:175], v206, s[98:99] offset:0
	global_load_dwordx4 v[176:179], v206, s[98:99] offset:64
	global_load_dwordx4 v[180:183], v206, s[98:99] offset:128
	global_load_dwordx4 v[184:187], v206, s[98:99] offset:192
	global_load_dwordx4 v[188:191], v207, s[98:99] offset:0
	global_load_dwordx4 v[192:195], v207, s[98:99] offset:64
	global_load_dwordx4 v[196:199], v207, s[98:99] offset:128
	global_load_dwordx4 v[200:203], v207, s[98:99] offset:192
	v_readlane_b32 s44, v252, 8
	v_readlane_b32 s45, v252, 9
	v_add_u32_e32 v50, s5, v167
	v_readlane_b32 s46, v252, 10
	v_readlane_b32 s47, v252, 11
	s_mov_b64 s[12:13], s[44:45]
	v_add_u32_e32 v48, 0xffffc000, v50
	v_ashrrev_i32_e32 v51, 31, v50
	v_cmp_gt_i32_e32 vcc, s18, v50
	s_mov_b64 s[14:15], s[46:47]
	v_mov_b32_e32 v76, s15
	v_cndmask_b32_e32 v49, 0, v51, vcc
	v_cndmask_b32_e32 v48, v48, v50, vcc
	v_mov_b32_e32 v77, s13
	v_mov_b32_e32 v78, s14
	v_mov_b32_e32 v79, s12
	s_ashr_i32 s5, s4, 31
	v_cndmask_b32_e32 v53, v76, v77, vcc
	v_cndmask_b32_e32 v52, v78, v79, vcc
	v_lshlrev_b64 v[48:49], 12, v[48:49]
	v_lshl_add_u64 v[48:49], v[52:53], 0, v[48:49]
	s_lshl_b64 s[4:5], s[4:5], 2
	v_lshl_add_u64 v[48:49], v[48:49], 0, s[4:5]
	v_lshlrev_b32_e32 v110, 2, v102
	v_lshl_add_u64 v[52:53], v[48:49], 0, v[110:111]
	v_lshlrev_b32_e32 v48, 2, v104
	v_mov_b32_e32 v49, v111
	v_lshl_add_u64 v[64:65], v[52:53], 0, v[48:49]
	s_nop 0
	s_nop 0
	s_nop 0
	s_nop 0
	s_nop 0
	v_readlane_b32 s48, v252, 12
	v_readlane_b32 s49, v252, 13
	v_readlane_b32 s50, v252, 14
	v_readlane_b32 s51, v252, 15
	v_readlane_b32 s52, v252, 16
	v_readlane_b32 s53, v252, 17
	v_readlane_b32 s54, v252, 18
	v_readlane_b32 s55, v252, 19
	v_readlane_b32 s56, v252, 20
	v_readlane_b32 s57, v252, 21
	v_readlane_b32 s58, v252, 22
	v_readlane_b32 s59, v252, 23
	v_or_b32_e32 v68, 16, v50
	v_add_u32_e32 v72, 0xffffc010, v50
	v_ashrrev_i32_e32 v69, 31, v68
	v_readlane_b32 s44, v251, 40
	v_cmp_gt_i32_e32 vcc, s18, v68
	v_lshlrev_b64 v[70:71], 12, v[50:51]
	v_readlane_b32 s52, v251, 48
	v_readlane_b32 s53, v251, 49
	v_cndmask_b32_e32 v73, 0, v69, vcc
	v_cndmask_b32_e32 v72, v72, v68, vcc
	v_lshl_add_u64 v[70:71], s[52:53], 0, v[70:71]
	v_cndmask_b32_e32 v75, v76, v77, vcc
	v_cndmask_b32_e32 v74, v78, v79, vcc
	v_lshlrev_b64 v[72:73], 12, v[72:73]
	v_lshl_add_u64 v[70:71], v[70:71], 0, s[4:5]
	v_lshl_add_u64 v[72:73], v[74:75], 0, v[72:73]
	v_lshl_add_u64 v[70:71], v[70:71], 0, v[110:111]
	v_lshl_add_u64 v[72:73], v[72:73], 0, s[4:5]
	v_lshl_add_u64 v[70:71], v[70:71], 0, v[48:49]
	v_lshl_add_u64 v[72:73], v[72:73], 0, v[110:111]
	v_lshl_add_u64 v[72:73], v[72:73], 0, v[48:49]
	v_add_u32_e32 v51, 0xffffc020, v50
	v_lshlrev_b64 v[68:69], 12, v[68:69]
	v_lshl_add_u64 v[68:69], s[52:53], 0, v[68:69]
	v_lshl_add_u64 v[68:69], v[68:69], 0, s[4:5]
	v_lshl_add_u64 v[68:69], v[68:69], 0, v[110:111]
	v_lshl_add_u64 v[68:69], v[68:69], 0, v[48:49]
	s_mov_b32 s8, 0
	v_readlane_b32 s45, v251, 41
	v_readlane_b32 s46, v251, 42
	v_readlane_b32 s47, v251, 43
	v_readlane_b32 s48, v251, 44
	v_readlane_b32 s49, v251, 45
	v_readlane_b32 s50, v251, 46
	v_readlane_b32 s51, v251, 47
	v_readlane_b32 s54, v251, 50
	v_readlane_b32 s55, v251, 51
	v_readlane_b32 s56, v251, 52
	v_readlane_b32 s57, v251, 53
	v_readlane_b32 s58, v251, 54
	v_readlane_b32 s59, v251, 55
	s_waitcnt vmcnt(12)
	v_pk_add_f32 v[52:53], v[92:93], v[80:81]
	v_pk_add_f32 v[54:55], v[94:95], v[82:83]
	s_nop 0
	v_pk_add_f32 v[56:57], v[88:89], v[120:121]
	v_pk_add_f32 v[58:59], v[90:91], v[122:123]
	s_nop 0
	v_pk_add_f32 v[60:61], v[84:85], v[124:125]
	v_pk_add_f32 v[62:63], v[86:87], v[126:127]
	s_nop 0
	v_pk_add_f32 v[64:65], v[150:151], v[134:135]
	v_pk_add_f32 v[66:67], v[152:153], v[136:137]
	global_store_dwordx4 v[70:71], v[52:55], off
	global_store_dwordx4 v[70:71], v[56:59], off offset:64
	global_store_dwordx4 v[70:71], v[60:63], off offset:128
	global_store_dwordx4 v[70:71], v[64:67], off offset:192
	s_nop 0
	s_nop 0
	s_nop 0
	s_nop 0
	s_nop 0
	v_or_b32_e32 v70, 32, v50
	v_ashrrev_i32_e32 v71, 31, v70
	v_cmp_gt_i32_e32 vcc, s18, v70
	s_waitcnt vmcnt(12)
	v_pk_add_f32 v[44:45], v[44:45], v[138:139]
	v_cndmask_b32_e32 v73, 0, v71, vcc
	v_cndmask_b32_e32 v72, v51, v70, vcc
	v_cndmask_b32_e32 v75, v76, v77, vcc
	v_cndmask_b32_e32 v74, v78, v79, vcc
	v_lshlrev_b64 v[72:73], 12, v[72:73]
	v_lshl_add_u64 v[72:73], v[74:75], 0, v[72:73]
	v_lshl_add_u64 v[72:73], v[72:73], 0, s[4:5]
	v_lshl_add_u64 v[72:73], v[72:73], 0, v[110:111]
	v_pk_add_f32 v[46:47], v[46:47], v[140:141]
	v_lshl_add_u64 v[72:73], v[72:73], 0, v[48:49]
	s_nop 0
	v_pk_add_f32 v[40:41], v[40:41], v[142:143]
	v_pk_add_f32 v[42:43], v[42:43], v[144:145]
	s_nop 0
	v_pk_add_f32 v[36:37], v[36:37], v[146:147]
	v_pk_add_f32 v[38:39], v[38:39], v[148:149]
	s_nop 0
	v_pk_add_f32 v[32:33], v[32:33], v[168:169]
	v_pk_add_f32 v[34:35], v[34:35], v[170:171]
	global_store_dwordx4 v[68:69], v[44:47], off
	global_store_dwordx4 v[68:69], v[40:43], off offset:64
	global_store_dwordx4 v[68:69], v[36:39], off offset:128
	global_store_dwordx4 v[68:69], v[32:35], off offset:192
	s_nop 0
	s_nop 0
	s_nop 0
	s_nop 0
	s_nop 0
	v_or_b32_e32 v52, 48, v50
	v_add_u32_e32 v54, 0xffffc030, v50
	v_ashrrev_i32_e32 v53, 31, v52
	v_cmp_gt_i32_e32 vcc, s18, v52
	v_lshlrev_b64 v[50:51], 12, v[70:71]
	v_lshl_add_u64 v[50:51], s[52:53], 0, v[50:51]
	v_cndmask_b32_e32 v55, 0, v53, vcc
	v_cndmask_b32_e32 v54, v54, v52, vcc
	v_cndmask_b32_e32 v57, v76, v77, vcc
	v_cndmask_b32_e32 v56, v78, v79, vcc
	v_lshlrev_b64 v[54:55], 12, v[54:55]
	v_lshl_add_u64 v[50:51], v[50:51], 0, s[4:5]
	v_lshl_add_u64 v[54:55], v[56:57], 0, v[54:55]
	v_lshl_add_u64 v[50:51], v[50:51], 0, v[110:111]
	v_lshl_add_u64 v[54:55], v[54:55], 0, s[4:5]
	v_lshl_add_u64 v[50:51], v[50:51], 0, v[48:49]
	v_lshl_add_u64 v[54:55], v[54:55], 0, v[110:111]
	v_lshl_add_u64 v[54:55], v[54:55], 0, v[48:49]
	s_waitcnt vmcnt(12)
	v_pk_add_f32 v[28:29], v[28:29], v[172:173]
	v_pk_add_f32 v[30:31], v[30:31], v[174:175]
	s_nop 0
	v_pk_add_f32 v[24:25], v[24:25], v[176:177]
	v_pk_add_f32 v[26:27], v[26:27], v[178:179]
	s_nop 0
	v_pk_add_f32 v[20:21], v[20:21], v[180:181]
	v_pk_add_f32 v[22:23], v[22:23], v[182:183]
	s_nop 0
	v_pk_add_f32 v[16:17], v[16:17], v[184:185]
	v_pk_add_f32 v[18:19], v[18:19], v[186:187]
	global_store_dwordx4 v[50:51], v[28:31], off
	global_store_dwordx4 v[50:51], v[24:27], off offset:64
	global_store_dwordx4 v[50:51], v[20:23], off offset:128
	global_store_dwordx4 v[50:51], v[16:19], off offset:192
	s_nop 0
	s_nop 0
	s_nop 0
	s_nop 0
	s_nop 0
	v_lshlrev_b64 v[32:33], 12, v[52:53]
	v_lshl_add_u64 v[32:33], s[52:53], 0, v[32:33]
	v_lshl_add_u64 v[32:33], v[32:33], 0, s[4:5]
	v_lshl_add_u64 v[32:33], v[32:33], 0, v[110:111]
	v_lshl_add_u64 v[32:33], v[32:33], 0, v[48:49]
	s_waitcnt vmcnt(12)
	v_pk_add_f32 v[12:13], v[12:13], v[188:189]
	v_pk_add_f32 v[14:15], v[14:15], v[190:191]
	s_nop 0
	v_pk_add_f32 v[8:9], v[8:9], v[192:193]
	v_pk_add_f32 v[10:11], v[10:11], v[194:195]
	s_nop 0
	v_pk_add_f32 v[4:5], v[4:5], v[196:197]
	v_pk_add_f32 v[6:7], v[6:7], v[198:199]
	s_nop 0
	v_pk_add_f32 v[0:1], v[0:1], v[200:201]
	v_pk_add_f32 v[2:3], v[2:3], v[202:203]
	global_store_dwordx4 v[32:33], v[12:15], off
	global_store_dwordx4 v[32:33], v[8:11], off offset:64
	global_store_dwordx4 v[32:33], v[4:7], off offset:128
	global_store_dwordx4 v[32:33], v[0:3], off offset:192
	s_mov_b64 s[4:5], -1
	s_cmp_gt_i32 s8, 3
	s_mov_b64 s[6:7], -1
	s_cbranch_scc1 .LBB0_681
